# speedup vs baseline: 1.0023x; 1.0023x over previous
.LBB0_572:
	s_waitcnt lgkmcnt(0)
	v_mfma_f32_32x32x16_bf16 v[80:95], v[112:115], v[96:99], 0
	s_and_b64 vcc, exec, s[2:3]
	v_mfma_f32_32x32x16_bf16 v[64:79], v[116:119], v[96:99], 0
	v_mfma_f32_32x32x16_bf16 v[80:95], v[120:123], v[100:103], v[80:95]
	v_mfma_f32_32x32x16_bf16 v[64:79], v[124:127], v[100:103], v[64:79]
	s_cbranch_vccnz .Lda_anym0
.LBB0_576:
	s_add_i32 s7, s12, 1
	s_and_b32 s10, s7, 3
	s_mulk_i32 s10, 0x5000
	s_add_i32 s10, s10, 0
	v_add_u32_e32 v144, s10, v251
	v_add_u32_e32 v224, v144, v165
	v_add_u32_e32 v177, v144, v247
	ds_read_b128 v[132:135], v224
	ds_read_b128 v[136:139], v224 offset:4096
	ds_read_b128 v[140:143], v177
	ds_read_b128 v[128:131], v177 offset:4096
	v_exp_f32_e32 v194, v80
	v_exp_f32_e32 v182, v64
	v_exp_f32_e32 v195, v82
	v_exp_f32_e32 v183, v66
	v_exp_f32_e32 v200, v81
	v_exp_f32_e32 v184, v65
	v_exp_f32_e32 v201, v83
	v_exp_f32_e32 v185, v67
	v_exp_f32_e32 v206, v84
	v_exp_f32_e32 v186, v68
	v_exp_f32_e32 v207, v86
	v_exp_f32_e32 v187, v70
	v_exp_f32_e32 v210, v85
	v_exp_f32_e32 v188, v69
	v_exp_f32_e32 v211, v87
	v_exp_f32_e32 v189, v71
	v_exp_f32_e32 v196, v88
	v_exp_f32_e32 v190, v72
	v_exp_f32_e32 v197, v90
	v_exp_f32_e32 v191, v74
	v_exp_f32_e32 v202, v89
	v_exp_f32_e32 v192, v73
	v_exp_f32_e32 v203, v91
	v_exp_f32_e32 v193, v75
	v_pk_add_f32 v[64:65], v[194:195], v[182:183]
	v_exp_f32_e32 v208, v92
	v_exp_f32_e32 v198, v76
	v_exp_f32_e32 v209, v94
	v_exp_f32_e32 v199, v78
	v_pk_add_f32 v[64:65], v[64:65], 0 op_sel_hi:[1,0]
	v_pk_add_f32 v[66:67], v[200:201], v[184:185]
	v_pk_add_f32 v[68:69], v[206:207], v[186:187]
	v_exp_f32_e32 v212, v93
	v_exp_f32_e32 v204, v77
	v_exp_f32_e32 v213, v95
	v_exp_f32_e32 v205, v79
	v_pk_add_f32 v[66:67], v[66:67], 0 op_sel_hi:[1,0]
	v_pk_add_f32 v[64:65], v[68:69], v[64:65]
	v_pk_add_f32 v[68:69], v[210:211], v[188:189]
	s_nop 0
	v_pk_add_f32 v[66:67], v[68:69], v[66:67]
	v_pk_add_f32 v[68:69], v[196:197], v[190:191]
	s_nop 0
	v_pk_add_f32 v[64:65], v[68:69], v[64:65]
	v_pk_add_f32 v[68:69], v[202:203], v[192:193]
	s_nop 0
	v_pk_add_f32 v[66:67], v[68:69], v[66:67]
	v_pk_add_f32 v[68:69], v[208:209], v[198:199]
	s_nop 0
	v_pk_add_f32 v[64:65], v[68:69], v[64:65]
	v_pk_add_f32 v[68:69], v[212:213], v[204:205]
	s_nop 0
	v_pk_add_f32 v[66:67], v[68:69], v[66:67]
	s_nop 0
	v_pk_add_f32 v[64:65], v[64:65], v[66:67]
	s_nop 0
	v_pk_add_f32 v[214:215], v[64:65], v[64:65] op_sel:[0,1] op_sel_hi:[1,0]
	s_nop 0
	v_cmp_ngt_f32_e32 vcc, s92, v214
	s_cbranch_vccnz .Lda_slow0
.LBB0_578:
	s_waitcnt lgkmcnt(0)
	v_mfma_f32_32x32x16_bf16 v[80:95], v[132:135], v[104:107], 0
	s_andn2_b64 vcc, exec, s[2:3]
	v_mfma_f32_32x32x16_bf16 v[64:79], v[136:139], v[104:107], 0
	v_mfma_f32_32x32x16_bf16 v[80:95], v[140:143], v[108:111], v[80:95]
	v_mfma_f32_32x32x16_bf16 v[64:79], v[128:131], v[108:111], v[64:79]
	s_cbranch_vccz .Lda_anym1

.LBB0_582:
	s_nop 4
	v_exp_f32_e32 v222, v80
	v_exp_f32_e32 v228, v64
	v_exp_f32_e32 v223, v82
	v_exp_f32_e32 v229, v66
	v_exp_f32_e32 v216, v81
	v_exp_f32_e32 v80, v65
	v_exp_f32_e32 v217, v83
	v_exp_f32_e32 v81, v67
	v_exp_f32_e32 v64, v84
	v_exp_f32_e32 v230, v68
	v_exp_f32_e32 v65, v86
	v_exp_f32_e32 v231, v70
	v_exp_f32_e32 v218, v85
	v_exp_f32_e32 v82, v69
	v_exp_f32_e32 v219, v87
	v_exp_f32_e32 v83, v71
	v_exp_f32_e32 v68, v88
	v_exp_f32_e32 v232, v72
	v_exp_f32_e32 v69, v90
	v_exp_f32_e32 v233, v74
	v_exp_f32_e32 v86, v89
	v_exp_f32_e32 v84, v73
	v_exp_f32_e32 v87, v91
	v_exp_f32_e32 v85, v75
	v_pk_add_f32 v[66:67], v[222:223], v[228:229]
	v_exp_f32_e32 v70, v92
	v_exp_f32_e32 v234, v76
	v_exp_f32_e32 v71, v94
	v_exp_f32_e32 v235, v78
	v_pk_add_f32 v[66:67], v[66:67], 0 op_sel_hi:[1,0]
	v_pk_add_f32 v[72:73], v[216:217], v[80:81]
	v_pk_add_f32 v[74:75], v[64:65], v[230:231]
	v_exp_f32_e32 v90, v93
	v_exp_f32_e32 v220, v77
	v_exp_f32_e32 v91, v95
	v_exp_f32_e32 v221, v79
	v_pk_add_f32 v[72:73], v[72:73], 0 op_sel_hi:[1,0]
	v_pk_add_f32 v[66:67], v[74:75], v[66:67]
	v_pk_add_f32 v[74:75], v[218:219], v[82:83]
	s_nop 0
	v_pk_add_f32 v[72:73], v[74:75], v[72:73]
	v_pk_add_f32 v[74:75], v[68:69], v[232:233]
	s_nop 0
	v_pk_add_f32 v[66:67], v[74:75], v[66:67]
	v_pk_add_f32 v[74:75], v[86:87], v[84:85]
	s_nop 0
	v_pk_add_f32 v[72:73], v[74:75], v[72:73]
	v_pk_add_f32 v[74:75], v[70:71], v[234:235]
	s_nop 0
	v_pk_add_f32 v[66:67], v[74:75], v[66:67]
	v_pk_add_f32 v[74:75], v[90:91], v[220:221]
	s_nop 0
	v_pk_add_f32 v[72:73], v[74:75], v[72:73]
	s_nop 0
	v_pk_add_f32 v[66:67], v[66:67], v[72:73]
	s_nop 0
	v_pk_add_f32 v[226:227], v[66:67], v[66:67] op_sel:[0,1] op_sel_hi:[1,0]
	s_nop 0
	v_cmp_ngt_f32_e32 vcc, s92, v226
	s_cbranch_vccnz .Lda_slow1

.LBB0_585:
	s_add_i32 s12, s12, 4
	s_cmp_ge_u32 s12, s19
	s_cselect_b64 s[10:11], -1, 0
	s_cbranch_scc1 .LBB0_587
	s_and_b32 s12, s12, 3
	s_mulk_i32 s12, 0x5000
	s_add_i32 s12, s14, s12
	s_mov_b32 m0, s12
	s_nop 0
	global_load_lds_dwordx4 v[180:181], off
	s_add_i32 m0, s12, 0x3000
	s_nop 0
	global_load_lds_dwordx4 v[178:179], off
.LBB0_587:
	v_cvt_pk_bf16_f32 v228, v194, v200
	v_cvt_pk_bf16_f32 v229, v195, v201
	v_cvt_pk_bf16_f32 v230, v206, v210
	v_cvt_pk_bf16_f32 v231, v207, v211
	v_cvt_pk_bf16_f32 v216, v66, v67
	v_cvt_pk_bf16_f32 v218, v88, v73
	v_cvt_pk_bf16_f32 v217, v72, v217
	v_cvt_pk_bf16_f32 v219, v94, v219
	s_waitcnt lgkmcnt(0)
	v_cvt_pk_bf16_f32 v92, v92, v75
	v_mfma_f32_32x32x16_bf16 v[32:47], v[156:159], v[228:231], v[32:47]
	v_cvt_pk_bf16_f32 v93, v86, v87
	v_cvt_pk_bf16_f32 v94, v222, v79
	v_cvt_pk_bf16_f32 v95, v224, v91
	v_cvt_pk_bf16_f32 v86, v182, v184
	v_cvt_pk_bf16_f32 v87, v183, v185
	v_cvt_pk_bf16_f32 v88, v186, v188
	v_cvt_pk_bf16_f32 v89, v187, v189
	v_mfma_f32_32x32x16_bf16 v[48:63], v[156:159], v[216:219], v[48:63]
	v_cvt_pk_bf16_f32 v64, v64, v65
	v_cvt_pk_bf16_f32 v65, v68, v81
	v_cvt_pk_bf16_f32 v66, v70, v69
	v_cvt_pk_bf16_f32 v67, v76, v83
	v_cvt_pk_bf16_f32 v68, v74, v71
	v_cvt_pk_bf16_f32 v69, v78, v85
	v_cvt_pk_bf16_f32 v70, v90, v77
	v_mfma_f32_32x32x16_bf16 v[0:15], v[152:155], v[228:231], v[0:15]
	v_cvt_pk_bf16_f32 v71, v220, v221
	s_and_b64 vcc, exec, s[10:11]
	v_mfma_f32_32x32x16_bf16 v[16:31], v[152:155], v[216:219], v[16:31]
	v_cvt_pk_bf16_f32 v152, v196, v202
	v_cvt_pk_bf16_f32 v153, v197, v203
	v_cvt_pk_bf16_f32 v154, v208, v212
	v_cvt_pk_bf16_f32 v155, v209, v213
	s_nop 1
	v_mfma_f32_32x32x16_bf16 v[32:47], v[148:151], v[152:155], v[32:47]
	v_mfma_f32_32x32x16_bf16 v[48:63], v[148:151], v[92:95], v[48:63]
	v_mfma_f32_32x32x16_bf16 v[0:15], v[144:147], v[152:155], v[0:15]
	v_mfma_f32_32x32x16_bf16 v[16:31], v[144:147], v[92:95], v[16:31]
	v_mfma_f32_32x32x16_bf16 v[32:47], v[140:143], v[86:89], v[32:47]
	v_mfma_f32_32x32x16_bf16 v[48:63], v[140:143], v[64:67], v[48:63]
	v_mfma_f32_32x32x16_bf16 v[0:15], v[136:139], v[86:89], v[0:15]
	v_mfma_f32_32x32x16_bf16 v[16:31], v[136:139], v[64:67], v[16:31]
	v_cvt_pk_bf16_f32 v64, v190, v192
	v_cvt_pk_bf16_f32 v65, v191, v193
	v_cvt_pk_bf16_f32 v66, v198, v204
	v_cvt_pk_bf16_f32 v67, v199, v205
	s_nop 1
	v_mfma_f32_32x32x16_bf16 v[32:47], v[132:135], v[64:67], v[32:47]
	v_mfma_f32_32x32x16_bf16 v[48:63], v[132:135], v[68:71], v[48:63]
	v_mfma_f32_32x32x16_bf16 v[0:15], v[128:131], v[64:67], v[0:15]
	v_mfma_f32_32x32x16_bf16 v[16:31], v[128:131], v[68:71], v[16:31]
	s_cbranch_vccnz .Lda_lastwait
	s_waitcnt vmcnt(2)
.Lda_bar:
	s_barrier
	v_add_f32_e32 v241, v241, v226
	v_add_f32_e32 v244, v244, v214
	v_lshl_add_u64 v[178:179], v[178:179], 0, s[76:77]
	s_cmp_lg_u32 s5, s7
	v_lshl_add_u64 v[180:181], v[180:181], 0, s[76:77]
	s_mov_b32 s12, s7
	s_cbranch_scc1 .LBB0_572
	s_branch .LBB0_593
.Lda_lastwait:
	s_waitcnt vmcnt(0)
	s_branch .Lda_bar
.Lda_anym0:
	s_nop 9
	v_sub_f32_e32 v95, v95, v174
	v_sub_f32_e32 v94, v94, v174
	v_sub_f32_e32 v93, v93, v174
	v_sub_f32_e32 v92, v92, v174
	v_sub_f32_e32 v91, v91, v174
	v_sub_f32_e32 v90, v90, v174
	v_sub_f32_e32 v89, v89, v174
	v_sub_f32_e32 v88, v88, v174
	v_sub_f32_e32 v87, v87, v174
	v_sub_f32_e32 v86, v86, v174
	v_sub_f32_e32 v85, v85, v174
	v_sub_f32_e32 v84, v84, v174
	v_sub_f32_e32 v83, v83, v174
	v_sub_f32_e32 v82, v82, v174
	v_sub_f32_e32 v81, v81, v174
	v_sub_f32_e32 v80, v80, v174
	v_sub_f32_e32 v79, v79, v174
	v_sub_f32_e32 v78, v78, v174
	v_sub_f32_e32 v77, v77, v174
	v_sub_f32_e32 v76, v76, v174
	v_sub_f32_e32 v75, v75, v174
	v_sub_f32_e32 v74, v74, v174
	v_sub_f32_e32 v73, v73, v174
	v_sub_f32_e32 v72, v72, v174
	v_sub_f32_e32 v71, v71, v174
	v_sub_f32_e32 v70, v70, v174
	v_sub_f32_e32 v69, v69, v174
	v_sub_f32_e32 v68, v68, v174
	v_sub_f32_e32 v67, v67, v174
	v_sub_f32_e32 v66, v66, v174
	v_sub_f32_e32 v65, v65, v174
	v_sub_f32_e32 v64, v64, v174
	s_branch .LBB0_576
.Lda_slow0:
	v_add_u32_e32 v80, v144, v166
	ds_read_b128 v[64:67], v80
	v_add_u32_e32 v148, v144, v168
	ds_read_b128 v[144:147], v148
	ds_read_b128 v[80:83], v80 offset:4096
	s_mov_b64 s[2:3], -1
	s_waitcnt lgkmcnt(0)
	v_mfma_f32_32x32x16_bf16 v[64:79], v[64:67], v[96:99], 0
	v_mfma_f32_32x32x16_bf16 v[64:79], v[144:147], v[100:103], v[64:79]
	ds_read_b128 v[144:147], v148 offset:4096
	v_mfma_f32_32x32x16_bf16 v[80:95], v[80:83], v[96:99], 0
	s_nop 9
	v_sub_f32_e32 v64, v64, v174
	v_sub_f32_e32 v67, v67, v174
	v_sub_f32_e32 v148, v70, v174
	v_sub_f32_e32 v149, v71, v174
	v_sub_f32_e32 v150, v72, v174
	v_sub_f32_e32 v73, v73, v174
	v_sub_f32_e32 v151, v74, v174
	s_waitcnt lgkmcnt(0)
	v_mfma_f32_32x32x16_bf16 v[80:95], v[144:147], v[100:103], v[80:95]
	v_sub_f32_e32 v145, v65, v174
	v_sub_f32_e32 v147, v69, v174
	v_sub_f32_e32 v152, v75, v174
	v_sub_f32_e32 v153, v76, v174
	v_sub_f32_e32 v154, v77, v174
	v_sub_f32_e32 v155, v78, v174
	v_sub_f32_e32 v156, v79, v174
	s_nop 4
	v_sub_f32_e32 v80, v80, v174
	v_sub_f32_e32 v81, v81, v174
	v_max_f32_e32 v144, v64, v80
	v_max_f32_e32 v65, v145, v81
	v_max3_f32 v65, v144, s93, v65
	v_sub_f32_e32 v144, v66, v174
	v_sub_f32_e32 v82, v82, v174
	v_sub_f32_e32 v83, v83, v174
	v_max_f32_e32 v66, v144, v82
	v_max_f32_e32 v146, v67, v83
	v_max3_f32 v65, v65, v66, v146
	v_sub_f32_e32 v146, v68, v174
	v_sub_f32_e32 v84, v84, v174
	v_sub_f32_e32 v85, v85, v174
	v_max_f32_e32 v66, v146, v84
	v_max_f32_e32 v68, v147, v85
	v_sub_f32_e32 v86, v86, v174
	v_sub_f32_e32 v87, v87, v174
	v_max3_f32 v65, v65, v66, v68
	v_max_f32_e32 v66, v148, v86
	v_max_f32_e32 v68, v149, v87
	v_sub_f32_e32 v88, v88, v174
	v_sub_f32_e32 v89, v89, v174
	v_max3_f32 v65, v65, v66, v68
	v_max_f32_e32 v66, v150, v88
	v_max_f32_e32 v68, v73, v89
	v_sub_f32_e32 v90, v90, v174
	v_sub_f32_e32 v91, v91, v174
	v_max3_f32 v65, v65, v66, v68
	v_max_f32_e32 v66, v151, v90
	v_max_f32_e32 v68, v152, v91
	v_sub_f32_e32 v92, v92, v174
	v_sub_f32_e32 v93, v93, v174
	v_max3_f32 v65, v65, v66, v68
	v_max_f32_e32 v66, v153, v92
	v_max_f32_e32 v68, v154, v93
	v_sub_f32_e32 v94, v94, v174
	v_sub_f32_e32 v95, v95, v174
	v_max3_f32 v65, v65, v66, v68
	v_max_f32_e32 v66, v155, v94
	v_max_f32_e32 v68, v156, v95
	v_max3_f32 v65, v65, v66, v68
	v_mov_b32_e32 v66, v65
	s_nop 1
	v_permlane32_swap_b32_e32 v65, v66
	v_max3_f32 v72, v65, v66, 0
	v_sub_f32_e32 v64, v64, v72
	v_exp_f32_e32 v194, v64
	v_sub_f32_e32 v64, v80, v72
	v_exp_f32_e32 v182, v64
	v_exp_f32_e64 v66, -v72
	v_add_f32_e32 v64, v194, v182
	v_add_f32_e32 v65, 0, v64
	v_sub_f32_e32 v64, v145, v72
	v_exp_f32_e32 v200, v64
	v_sub_f32_e32 v64, v81, v72
	v_exp_f32_e32 v184, v64
	v_sub_f32_e32 v64, v144, v72
	v_exp_f32_e32 v68, v64
	v_sub_f32_e32 v64, v82, v72
	v_exp_f32_e32 v64, v64
	v_add_f32_e32 v69, v200, v184
	v_mul_f32_e32 v244, v244, v66
	v_pk_mul_f32 v[46:47], v[46:47], v[66:67] op_sel_hi:[1,0]
	v_pk_add_f32 v[70:71], v[68:69], v[64:65]
	v_sub_f32_e32 v65, v67, v72
	v_exp_f32_e32 v201, v65
	v_sub_f32_e32 v65, v83, v72
	v_exp_f32_e32 v185, v65
	v_sub_f32_e32 v65, v146, v72
	v_pk_add_f32 v[186:187], v[70:71], v[70:71] op_sel_hi:[0,1]
	v_exp_f32_e32 v206, v65
	v_sub_f32_e32 v65, v84, v72
	v_exp_f32_e32 v186, v65
	v_sub_f32_e32 v65, v147, v72
	v_add_f32_e32 v207, v201, v185
	v_exp_f32_e32 v210, v65
	v_sub_f32_e32 v65, v85, v72
	v_pk_add_f32 v[70:71], v[206:207], v[186:187]
	v_exp_f32_e32 v188, v65
	v_sub_f32_e32 v65, v148, v72
	v_pk_add_f32 v[70:71], v[70:71], v[70:71] op_sel_hi:[0,1]
	v_exp_f32_e32 v74, v65
	v_sub_f32_e32 v65, v86, v72
	v_exp_f32_e32 v70, v65
	v_sub_f32_e32 v65, v149, v72
	v_add_f32_e32 v75, v210, v188
	v_exp_f32_e32 v211, v65
	v_sub_f32_e32 v65, v87, v72
	v_pk_add_f32 v[76:77], v[74:75], v[70:71]
	v_exp_f32_e32 v189, v65
	v_sub_f32_e32 v65, v150, v72
	v_pk_add_f32 v[190:191], v[76:77], v[76:77] op_sel_hi:[0,1]
	v_exp_f32_e32 v196, v65
	v_sub_f32_e32 v65, v88, v72
	v_exp_f32_e32 v190, v65
	v_sub_f32_e32 v65, v73, v72
	v_add_f32_e32 v197, v211, v189
	v_exp_f32_e32 v202, v65
	v_sub_f32_e32 v65, v89, v72
	v_pk_add_f32 v[76:77], v[196:197], v[190:191]
	v_exp_f32_e32 v192, v65
	v_sub_f32_e32 v65, v151, v72
	v_pk_add_f32 v[76:77], v[76:77], v[76:77] op_sel_hi:[0,1]
	v_exp_f32_e32 v78, v65
	v_sub_f32_e32 v65, v90, v72
	v_exp_f32_e32 v76, v65
	v_sub_f32_e32 v65, v152, v72
	v_add_f32_e32 v79, v202, v192
	v_exp_f32_e32 v203, v65
	v_sub_f32_e32 v65, v91, v72
	v_pk_add_f32 v[80:81], v[78:79], v[76:77]
	v_exp_f32_e32 v193, v65
	v_sub_f32_e32 v65, v153, v72
	v_pk_add_f32 v[198:199], v[80:81], v[80:81] op_sel_hi:[0,1]
	v_exp_f32_e32 v208, v65
	v_sub_f32_e32 v65, v92, v72
	v_exp_f32_e32 v198, v65
	v_sub_f32_e32 v65, v154, v72
	v_add_f32_e32 v209, v203, v193
	v_exp_f32_e32 v212, v65
	v_sub_f32_e32 v65, v93, v72
	v_pk_add_f32 v[80:81], v[208:209], v[198:199]
	v_exp_f32_e32 v204, v65
	v_sub_f32_e32 v65, v155, v72
	v_pk_add_f32 v[80:81], v[80:81], v[80:81] op_sel_hi:[0,1]
	v_exp_f32_e32 v82, v65
	v_sub_f32_e32 v65, v94, v72
	v_exp_f32_e32 v80, v65
	v_sub_f32_e32 v65, v156, v72
	v_exp_f32_e32 v213, v65
	v_sub_f32_e32 v65, v95, v72
	v_exp_f32_e32 v205, v65
	v_add_f32_e32 v83, v212, v204
	v_pk_add_f32 v[84:85], v[82:83], v[80:81]
	v_pk_mul_f32 v[44:45], v[44:45], v[66:67] op_sel_hi:[1,0]
	v_pk_add_f32 v[84:85], v[84:85], v[84:85] op_sel_hi:[0,1]
	v_add_f32_e32 v175, v213, v205
	v_mov_b32_e32 v73, v85
	v_pk_add_f32 v[174:175], v[174:175], v[72:73]
	v_pk_mul_f32 v[42:43], v[42:43], v[66:67] op_sel_hi:[1,0]
	v_pk_mul_f32 v[40:41], v[40:41], v[66:67] op_sel_hi:[1,0]
	v_pk_mul_f32 v[38:39], v[38:39], v[66:67] op_sel_hi:[1,0]
	v_pk_mul_f32 v[36:37], v[36:37], v[66:67] op_sel_hi:[1,0]
	v_pk_mul_f32 v[34:35], v[34:35], v[66:67] op_sel_hi:[1,0]
	v_pk_mul_f32 v[32:33], v[32:33], v[66:67] op_sel_hi:[1,0]
	v_pk_mul_f32 v[14:15], v[14:15], v[66:67] op_sel_hi:[1,0]
	v_pk_mul_f32 v[12:13], v[12:13], v[66:67] op_sel_hi:[1,0]
	v_pk_mul_f32 v[10:11], v[10:11], v[66:67] op_sel_hi:[1,0]
	v_pk_mul_f32 v[8:9], v[8:9], v[66:67] op_sel_hi:[1,0]
	v_pk_mul_f32 v[6:7], v[6:7], v[66:67] op_sel_hi:[1,0]
	v_pk_mul_f32 v[4:5], v[4:5], v[66:67] op_sel_hi:[1,0]
	v_pk_mul_f32 v[2:3], v[2:3], v[66:67] op_sel_hi:[1,0]
	v_pk_mul_f32 v[0:1], v[0:1], v[66:67] op_sel_hi:[1,0]
	v_mov_b32_e32 v195, v68
	v_mov_b32_e32 v207, v74
	v_mov_b32_e32 v197, v78
	v_mov_b32_e32 v209, v82
	v_mov_b32_e32 v183, v64
	v_mov_b32_e32 v187, v70
	v_mov_b32_e32 v191, v76
	v_mov_b32_e32 v199, v80
	v_mov_b32_e32 v214, v175
	s_branch .LBB0_578
.Lda_anym1:
	s_nop 9
	v_sub_f32_e32 v95, v95, v176
	v_sub_f32_e32 v94, v94, v176
	v_sub_f32_e32 v93, v93, v176
	v_sub_f32_e32 v92, v92, v176
	v_sub_f32_e32 v91, v91, v176
	v_sub_f32_e32 v90, v90, v176
	v_sub_f32_e32 v89, v89, v176
	v_sub_f32_e32 v88, v88, v176
	v_sub_f32_e32 v87, v87, v176
	v_sub_f32_e32 v86, v86, v176
	v_sub_f32_e32 v85, v85, v176
	v_sub_f32_e32 v84, v84, v176
	v_sub_f32_e32 v83, v83, v176
	v_sub_f32_e32 v82, v82, v176
	v_sub_f32_e32 v81, v81, v176
	v_sub_f32_e32 v80, v80, v176
	v_sub_f32_e32 v79, v79, v176
	v_sub_f32_e32 v78, v78, v176
	v_sub_f32_e32 v77, v77, v176
	v_sub_f32_e32 v76, v76, v176
	v_sub_f32_e32 v75, v75, v176
	v_sub_f32_e32 v74, v74, v176
	v_sub_f32_e32 v73, v73, v176
	v_sub_f32_e32 v72, v72, v176
	v_sub_f32_e32 v71, v71, v176
	v_sub_f32_e32 v70, v70, v176
	v_sub_f32_e32 v69, v69, v176
	v_sub_f32_e32 v68, v68, v176
	v_sub_f32_e32 v67, v67, v176
	v_sub_f32_e32 v66, v66, v176
	v_sub_f32_e32 v65, v65, v176
	v_sub_f32_e32 v64, v64, v176
	s_branch .LBB0_580
.Lda_slow1:
	ds_read_b128 v[64:67], v224
	ds_read_b128 v[216:219], v177
	ds_read_b128 v[80:83], v224 offset:4096
	s_mov_b64 s[2:3], -1
	s_waitcnt lgkmcnt(0)
	v_mfma_f32_32x32x16_bf16 v[64:79], v[64:67], v[104:107], 0
	v_mfma_f32_32x32x16_bf16 v[64:79], v[216:219], v[108:111], v[64:79]
	ds_read_b128 v[216:219], v177 offset:4096
	v_mfma_f32_32x32x16_bf16 v[80:95], v[80:83], v[104:107], 0
	s_nop 9
	v_sub_f32_e32 v64, v64, v176
	v_sub_f32_e32 v65, v65, v176
	v_sub_f32_e32 v215, v67, v176
	v_sub_f32_e32 v220, v72, v176
	v_sub_f32_e32 v222, v73, v176
	v_sub_f32_e32 v224, v74, v176
	v_sub_f32_e32 v225, v75, v176
	s_waitcnt lgkmcnt(0)
	v_mfma_f32_32x32x16_bf16 v[80:95], v[216:219], v[108:111], v[80:95]
	v_sub_f32_e32 v216, v69, v176
	v_sub_f32_e32 v218, v70, v176
	v_sub_f32_e32 v219, v71, v176
	v_sub_f32_e32 v228, v76, v176
	v_sub_f32_e32 v230, v77, v176
	v_sub_f32_e32 v232, v78, v176
	v_sub_f32_e32 v234, v79, v176
	s_nop 4
	v_sub_f32_e32 v80, v80, v176
	v_sub_f32_e32 v81, v81, v176
	v_max_f32_e32 v175, v64, v80
	v_max_f32_e32 v177, v65, v81
	v_max3_f32 v175, v175, s93, v177
	v_sub_f32_e32 v177, v66, v176
	v_sub_f32_e32 v82, v82, v176
	v_sub_f32_e32 v83, v83, v176
	v_max_f32_e32 v66, v177, v82
	v_max_f32_e32 v67, v215, v83
	v_max3_f32 v66, v175, v66, v67
	v_sub_f32_e32 v175, v68, v176
	v_sub_f32_e32 v84, v84, v176
	v_sub_f32_e32 v85, v85, v176
	v_max_f32_e32 v67, v175, v84
	v_max_f32_e32 v68, v216, v85
	v_sub_f32_e32 v86, v86, v176
	v_sub_f32_e32 v87, v87, v176
	v_max3_f32 v66, v66, v67, v68
	v_max_f32_e32 v67, v218, v86
	v_max_f32_e32 v68, v219, v87
	v_sub_f32_e32 v221, v88, v176
	v_sub_f32_e32 v223, v89, v176
	v_max3_f32 v66, v66, v67, v68
	v_max_f32_e32 v67, v220, v221
	v_max_f32_e32 v68, v222, v223
	v_sub_f32_e32 v90, v90, v176
	v_sub_f32_e32 v227, v91, v176
	v_max3_f32 v66, v66, v67, v68
	v_max_f32_e32 v67, v224, v90
	v_max_f32_e32 v68, v225, v227
	v_sub_f32_e32 v229, v92, v176
	v_sub_f32_e32 v231, v93, v176
	v_max3_f32 v66, v66, v67, v68
	v_max_f32_e32 v67, v228, v229
	v_max_f32_e32 v68, v230, v231
	v_sub_f32_e32 v233, v94, v176
	v_sub_f32_e32 v235, v95, v176
	v_max3_f32 v66, v66, v67, v68
	v_max_f32_e32 v67, v232, v233
	v_max_f32_e32 v68, v234, v235
	v_max3_f32 v66, v66, v67, v68
	v_mov_b32_e32 v67, v66
	s_nop 1
	v_permlane32_swap_b32_e32 v66, v67
	v_max3_f32 v226, v66, v67, 0
	v_sub_f32_e32 v64, v64, v226
	v_exp_f32_e32 v66, v64
	v_sub_f32_e32 v64, v80, v226
	v_sub_f32_e32 v65, v65, v226
	v_exp_f32_e32 v64, v64
	v_exp_f32_e32 v67, v65
	v_sub_f32_e32 v65, v81, v226
	v_sub_f32_e32 v68, v177, v226
	v_exp_f32_e32 v65, v65
	v_exp_f32_e32 v72, v68
	v_sub_f32_e32 v68, v82, v226
	v_exp_f32_e32 v68, v68
	v_add_f32_e32 v69, v66, v64
	v_add_f32_e32 v69, 0, v69
	v_add_f32_e32 v73, v67, v65
	v_pk_add_f32 v[70:71], v[72:73], v[68:69]
	v_sub_f32_e32 v69, v215, v226
	v_exp_f32_e32 v217, v69
	v_sub_f32_e32 v69, v83, v226
	v_exp_f32_e32 v81, v69
	v_sub_f32_e32 v69, v175, v226
	v_pk_add_f32 v[70:71], v[70:71], v[70:71] op_sel_hi:[0,1]
	v_exp_f32_e32 v88, v69
	v_sub_f32_e32 v69, v84, v226
	v_exp_f32_e32 v70, v69
	v_add_f32_e32 v89, v217, v81
	v_sub_f32_e32 v69, v216, v226
	v_exp_f32_e32 v73, v69
	v_pk_add_f32 v[74:75], v[88:89], v[70:71]
	v_sub_f32_e32 v69, v85, v226
	v_sub_f32_e32 v71, v218, v226
	v_pk_add_f32 v[76:77], v[74:75], v[74:75] op_sel_hi:[0,1]
	v_exp_f32_e32 v69, v69
	v_exp_f32_e32 v94, v71
	v_sub_f32_e32 v71, v86, v226
	v_exp_f32_e32 v76, v71
	v_sub_f32_e32 v71, v219, v226
	v_add_f32_e32 v95, v73, v69
	v_exp_f32_e32 v219, v71
	v_sub_f32_e32 v71, v87, v226
	v_pk_add_f32 v[74:75], v[94:95], v[76:77]
	v_exp_f32_e32 v83, v71
	v_sub_f32_e32 v71, v220, v226
	v_pk_add_f32 v[74:75], v[74:75], v[74:75] op_sel_hi:[0,1]
	v_exp_f32_e32 v92, v71
	v_sub_f32_e32 v71, v221, v226
	v_exp_f32_e32 v74, v71
	v_add_f32_e32 v93, v219, v83
	v_sub_f32_e32 v71, v222, v226
	v_sub_f32_e32 v77, v224, v226
	v_pk_add_f32 v[78:79], v[92:93], v[74:75]
	v_exp_f32_e32 v75, v71
	v_sub_f32_e32 v71, v223, v226
	v_pk_add_f32 v[78:79], v[78:79], v[78:79] op_sel_hi:[0,1]
	v_exp_f32_e32 v71, v71
	v_exp_f32_e32 v86, v77
	v_sub_f32_e32 v77, v90, v226
	v_exp_f32_e32 v78, v77
	v_add_f32_e32 v87, v75, v71
	v_sub_f32_e32 v77, v225, v226
	v_sub_f32_e32 v80, v232, v226
	v_pk_add_f32 v[84:85], v[86:87], v[78:79]
	v_exp_f32_e32 v87, v77
	v_sub_f32_e32 v77, v227, v226
	v_pk_add_f32 v[90:91], v[84:85], v[84:85] op_sel_hi:[0,1]
	v_exp_f32_e32 v85, v77
	v_sub_f32_e32 v77, v228, v226
	v_exp_f32_e32 v222, v77
	v_sub_f32_e32 v77, v229, v226
	v_exp_f32_e32 v90, v77
	v_add_f32_e32 v223, v87, v85
	v_sub_f32_e32 v77, v230, v226
	v_exp_f32_e32 v79, v77
	v_pk_add_f32 v[220:221], v[222:223], v[90:91]
	v_sub_f32_e32 v77, v231, v226
	v_pk_add_f32 v[220:221], v[220:221], v[220:221] op_sel_hi:[0,1]
	v_exp_f32_e32 v224, v80
	v_sub_f32_e32 v80, v233, v226
	v_exp_f32_e32 v77, v77
	v_exp_f32_e32 v220, v80
	v_sub_f32_e32 v80, v234, v226
	v_sub_f32_e32 v82, v235, v226
	v_add_f32_e32 v225, v79, v77
	v_pk_add_f32 v[228:229], v[224:225], v[220:221]
	v_exp_f32_e32 v91, v80
	v_exp_f32_e32 v221, v82
	v_exp_f32_e64 v80, -v226
	v_pk_add_f32 v[228:229], v[228:229], v[228:229] op_sel_hi:[0,1]
	v_mov_b32_e32 v227, v229
	v_add_f32_e32 v177, v91, v221
	v_pk_add_f32 v[176:177], v[176:177], v[226:227]
	v_mul_f32_e32 v241, v241, v80
	v_pk_mul_f32 v[62:63], v[62:63], v[80:81] op_sel_hi:[1,0]
	v_pk_mul_f32 v[60:61], v[60:61], v[80:81] op_sel_hi:[1,0]
	v_pk_mul_f32 v[58:59], v[58:59], v[80:81] op_sel_hi:[1,0]
	v_pk_mul_f32 v[56:57], v[56:57], v[80:81] op_sel_hi:[1,0]
	v_pk_mul_f32 v[54:55], v[54:55], v[80:81] op_sel_hi:[1,0]
	v_pk_mul_f32 v[52:53], v[52:53], v[80:81] op_sel_hi:[1,0]
	v_pk_mul_f32 v[50:51], v[50:51], v[80:81] op_sel_hi:[1,0]
	v_pk_mul_f32 v[48:49], v[48:49], v[80:81] op_sel_hi:[1,0]
	v_pk_mul_f32 v[30:31], v[30:31], v[80:81] op_sel_hi:[1,0]
	v_pk_mul_f32 v[28:29], v[28:29], v[80:81] op_sel_hi:[1,0]
	v_pk_mul_f32 v[26:27], v[26:27], v[80:81] op_sel_hi:[1,0]
	v_pk_mul_f32 v[24:25], v[24:25], v[80:81] op_sel_hi:[1,0]
	v_pk_mul_f32 v[22:23], v[22:23], v[80:81] op_sel_hi:[1,0]
	v_pk_mul_f32 v[20:21], v[20:21], v[80:81] op_sel_hi:[1,0]
	v_pk_mul_f32 v[18:19], v[18:19], v[80:81] op_sel_hi:[1,0]
	v_pk_mul_f32 v[16:17], v[16:17], v[80:81] op_sel_hi:[1,0]
	v_mov_b32_e32 v226, v177
	s_branch .LBB0_585

.Lgq_anym:
	s_nop 9
	v_sub_f32_e32 v63, v63, v147
	v_sub_f32_e32 v62, v62, v147
	v_sub_f32_e32 v61, v61, v147
	v_sub_f32_e32 v60, v60, v147
	v_sub_f32_e32 v59, v59, v147
	v_sub_f32_e32 v58, v58, v147
	v_sub_f32_e32 v57, v57, v147
	v_sub_f32_e32 v56, v56, v147
	v_sub_f32_e32 v55, v55, v147
	v_sub_f32_e32 v54, v54, v147
	v_sub_f32_e32 v53, v53, v147
	v_sub_f32_e32 v52, v52, v147
	v_sub_f32_e32 v51, v51, v147
	v_sub_f32_e32 v50, v50, v147
	v_sub_f32_e32 v49, v49, v147
	v_sub_f32_e32 v48, v48, v147
	v_sub_f32_e32 v47, v47, v147
	v_sub_f32_e32 v46, v46, v147
	v_sub_f32_e32 v45, v45, v147
	v_sub_f32_e32 v44, v44, v147
	v_sub_f32_e32 v43, v43, v147
	v_sub_f32_e32 v42, v42, v147
	v_sub_f32_e32 v41, v41, v147
	v_sub_f32_e32 v40, v40, v147
	v_sub_f32_e32 v39, v39, v147
	v_sub_f32_e32 v38, v38, v147
	v_sub_f32_e32 v37, v37, v147
	v_sub_f32_e32 v36, v36, v147
	v_sub_f32_e32 v35, v35, v147
	v_sub_f32_e32 v34, v34, v147
	v_sub_f32_e32 v33, v33, v147
	v_sub_f32_e32 v32, v32, v147
	s_branch .LBB0_649
.Lgq_slow:
	v_add_u32_e32 v146, s10, v163
	v_add_u32_e32 v48, v146, v165
	ds_read_b128 v[32:35], v48
	v_add_u32_e32 v156, v146, v172
	ds_read_b128 v[152:155], v156
	ds_read_b128 v[48:51], v48 offset:4096
	s_mov_b64 s[2:3], -1
	s_waitcnt lgkmcnt(0)
	v_mfma_f32_32x32x16_bf16 v[32:47], v[32:35], v[68:71], 0
	v_mfma_f32_32x32x16_bf16 v[32:47], v[152:155], v[64:67], v[32:47]
	ds_read_b128 v[152:155], v156 offset:4096
	v_add_u32_e32 v156, v146, v168
	v_add_u32_e32 v146, v146, v167
	v_mfma_f32_32x32x16_bf16 v[48:63], v[48:51], v[68:71], 0
	s_waitcnt lgkmcnt(0)
	v_mfma_f32_32x32x16_bf16 v[48:63], v[152:155], v[64:67], v[48:63]
	ds_read_b128 v[152:155], v156
	s_waitcnt lgkmcnt(0)
	v_mfma_f32_32x32x16_bf16 v[32:47], v[152:155], v[76:79], v[32:47]
	ds_read_b128 v[152:155], v156 offset:4096
	s_waitcnt lgkmcnt(0)
	v_mfma_f32_32x32x16_bf16 v[48:63], v[152:155], v[76:79], v[48:63]
	ds_read_b128 v[152:155], v146
	s_waitcnt lgkmcnt(0)
	v_mfma_f32_32x32x16_bf16 v[32:47], v[152:155], v[72:75], v[32:47]
	ds_read_b128 v[152:155], v146 offset:4096
	s_waitcnt lgkmcnt(0)
	v_mfma_f32_32x32x16_bf16 v[48:63], v[152:155], v[72:75], v[48:63]
	s_nop 8
	v_sub_f32_e32 v32, v32, v147
	v_sub_f32_e32 v33, v33, v147
	v_sub_f32_e32 v34, v34, v147
	v_sub_f32_e32 v153, v35, v147
	v_sub_f32_e32 v36, v36, v147
	v_sub_f32_e32 v158, v37, v147
	v_sub_f32_e32 v38, v38, v147
	v_sub_f32_e32 v48, v48, v147
	v_sub_f32_e32 v49, v49, v147
	v_max_f32_e32 v146, v32, v48
	v_max_f32_e32 v152, v33, v49
	v_sub_f32_e32 v50, v50, v147
	v_sub_f32_e32 v51, v51, v147
	v_max3_f32 v146, v146, s93, v152
	v_max_f32_e32 v152, v34, v50
	v_max_f32_e32 v35, v153, v51
	v_sub_f32_e32 v52, v52, v147
	v_sub_f32_e32 v53, v53, v147
	v_max3_f32 v35, v146, v152, v35
	v_max_f32_e32 v146, v36, v52
	v_max_f32_e32 v37, v158, v53
	v_max3_f32 v35, v35, v146, v37
	v_sub_f32_e32 v54, v54, v147
	v_sub_f32_e32 v146, v39, v147
	v_sub_f32_e32 v55, v55, v147
	v_max_f32_e32 v37, v38, v54
	v_max_f32_e32 v39, v146, v55
	v_sub_f32_e32 v40, v40, v147
	v_sub_f32_e32 v56, v56, v147
	v_sub_f32_e32 v179, v41, v147
	v_sub_f32_e32 v57, v57, v147
	v_max3_f32 v35, v35, v37, v39
	v_max_f32_e32 v37, v40, v56
	v_max_f32_e32 v39, v179, v57
	v_sub_f32_e32 v42, v42, v147
	v_sub_f32_e32 v186, v58, v147
	v_sub_f32_e32 v187, v43, v147
	v_sub_f32_e32 v59, v59, v147
	v_max3_f32 v35, v35, v37, v39
	v_max_f32_e32 v37, v42, v186
	v_max_f32_e32 v39, v187, v59
	v_sub_f32_e32 v44, v44, v147
	v_sub_f32_e32 v188, v60, v147
	v_sub_f32_e32 v189, v45, v147
	v_sub_f32_e32 v190, v61, v147
	v_max3_f32 v35, v35, v37, v39
	v_max_f32_e32 v37, v44, v188
	v_max_f32_e32 v39, v189, v190
	v_sub_f32_e32 v191, v46, v147
	v_sub_f32_e32 v192, v62, v147
	v_sub_f32_e32 v193, v47, v147
	v_sub_f32_e32 v194, v63, v147
	v_max3_f32 v35, v35, v37, v39
	v_max_f32_e32 v37, v191, v192
	v_max_f32_e32 v39, v193, v194
	v_max3_f32 v35, v35, v37, v39
	v_mov_b32_e32 v37, v35
	s_nop 1
	v_permlane32_swap_b32_e32 v35, v37
	v_max3_f32 v195, v35, v37, 0
	v_sub_f32_e32 v32, v32, v195
	v_sub_f32_e32 v33, v33, v195
	v_exp_f32_e32 v152, v32
	v_sub_f32_e32 v32, v48, v195
	v_exp_f32_e32 v154, v33
	v_sub_f32_e32 v33, v49, v195
	v_exp_f32_e32 v32, v32
	v_exp_f32_e32 v48, v33
	v_sub_f32_e32 v33, v34, v195
	v_exp_f32_e32 v60, v33
	v_sub_f32_e32 v33, v50, v195
	v_exp_f32_e32 v46, v33
	v_add_f32_e32 v35, v152, v32
	v_sub_f32_e32 v33, v153, v195
	v_add_f32_e32 v47, 0, v35
	v_add_f32_e32 v61, v154, v48
	v_exp_f32_e32 v155, v33
	v_sub_f32_e32 v33, v51, v195
	v_pk_add_f32 v[34:35], v[60:61], v[46:47]
	v_exp_f32_e32 v49, v33
	v_sub_f32_e32 v33, v36, v195
	v_pk_add_f32 v[34:35], v[34:35], v[34:35] op_sel_hi:[0,1]
	v_exp_f32_e32 v156, v33
	v_sub_f32_e32 v33, v52, v195
	v_exp_f32_e32 v34, v33
	v_add_f32_e32 v157, v155, v49
	v_sub_f32_e32 v33, v158, v195
	v_exp_f32_e32 v158, v33
	v_pk_add_f32 v[36:37], v[156:157], v[34:35]
	v_sub_f32_e32 v33, v53, v195
	v_pk_add_f32 v[62:63], v[36:37], v[36:37] op_sel_hi:[0,1]
	v_exp_f32_e32 v36, v33
	v_sub_f32_e32 v33, v38, v195
	v_exp_f32_e32 v180, v33
	v_sub_f32_e32 v33, v54, v195
	v_exp_f32_e32 v62, v33
	v_sub_f32_e32 v33, v146, v195
	v_add_f32_e32 v181, v158, v36
	v_exp_f32_e32 v159, v33
	v_sub_f32_e32 v33, v55, v195
	v_pk_add_f32 v[38:39], v[180:181], v[62:63]
	v_exp_f32_e32 v37, v33
	v_sub_f32_e32 v33, v40, v195
	v_pk_add_f32 v[38:39], v[38:39], v[38:39] op_sel_hi:[0,1]
	v_exp_f32_e32 v50, v33
	v_sub_f32_e32 v33, v56, v195
	v_exp_f32_e32 v38, v33
	v_add_f32_e32 v51, v159, v37
	v_sub_f32_e32 v33, v179, v195
	v_exp_f32_e32 v52, v33
	v_pk_add_f32 v[40:41], v[50:51], v[38:39]
	v_sub_f32_e32 v33, v57, v195
	v_pk_add_f32 v[182:183], v[40:41], v[40:41] op_sel_hi:[0,1]
	v_exp_f32_e32 v40, v33
	v_sub_f32_e32 v33, v42, v195
	v_exp_f32_e32 v184, v33
	v_sub_f32_e32 v33, v186, v195
	v_exp_f32_e32 v182, v33
	v_sub_f32_e32 v33, v187, v195
	v_add_f32_e32 v185, v52, v40
	v_exp_f32_e32 v53, v33
	v_sub_f32_e32 v33, v59, v195
	v_pk_add_f32 v[42:43], v[184:185], v[182:183]
	v_exp_f32_e32 v41, v33
	v_sub_f32_e32 v33, v44, v195
	v_pk_add_f32 v[42:43], v[42:43], v[42:43] op_sel_hi:[0,1]
	v_exp_f32_e32 v54, v33
	v_sub_f32_e32 v33, v188, v195
	v_exp_f32_e32 v42, v33
	v_add_f32_e32 v55, v53, v41
	v_sub_f32_e32 v33, v189, v195
	v_exp_f32_e32 v56, v33
	v_pk_add_f32 v[44:45], v[54:55], v[42:43]
	v_sub_f32_e32 v33, v190, v195
	v_pk_add_f32 v[186:187], v[44:45], v[44:45] op_sel_hi:[0,1]
	v_exp_f32_e32 v44, v33
	v_sub_f32_e32 v33, v191, v195
	v_exp_f32_e32 v188, v33
	v_sub_f32_e32 v33, v192, v195
	v_exp_f32_e32 v186, v33
	v_sub_f32_e32 v33, v193, v195
	v_exp_f32_e32 v57, v33
	v_sub_f32_e32 v33, v194, v195
	v_exp_f32_e32 v45, v33
	v_exp_f32_e64 v58, -v195
	v_add_f32_e32 v189, v56, v44
	v_pk_add_f32 v[190:191], v[188:189], v[186:187]
	v_add_f32_e32 v146, v57, v45
	v_pk_add_f32 v[190:191], v[190:191], v[190:191] op_sel:[0,1] op_sel_hi:[1,0]
	v_pk_mul_f32 v[30:31], v[30:31], v[58:59] op_sel_hi:[1,0]
	v_mov_b32_e32 v191, v195
	v_pk_mul_f32 v[28:29], v[28:29], v[58:59] op_sel_hi:[1,0]
	v_pk_mul_f32 v[26:27], v[26:27], v[58:59] op_sel_hi:[1,0]
	v_pk_mul_f32 v[24:25], v[24:25], v[58:59] op_sel_hi:[1,0]
	v_pk_mul_f32 v[22:23], v[22:23], v[58:59] op_sel_hi:[1,0]
	v_pk_mul_f32 v[20:21], v[20:21], v[58:59] op_sel_hi:[1,0]
	v_pk_mul_f32 v[18:19], v[18:19], v[58:59] op_sel_hi:[1,0]
	v_pk_mul_f32 v[16:17], v[16:17], v[58:59] op_sel_hi:[1,0]
	v_pk_mul_f32 v[14:15], v[14:15], v[58:59] op_sel_hi:[1,0]
	v_pk_mul_f32 v[12:13], v[12:13], v[58:59] op_sel_hi:[1,0]
	v_pk_mul_f32 v[10:11], v[10:11], v[58:59] op_sel_hi:[1,0]
	v_pk_mul_f32 v[8:9], v[8:9], v[58:59] op_sel_hi:[1,0]
	v_pk_mul_f32 v[6:7], v[6:7], v[58:59] op_sel_hi:[1,0]
	v_pk_mul_f32 v[4:5], v[4:5], v[58:59] op_sel_hi:[1,0]
	v_pk_mul_f32 v[2:3], v[2:3], v[58:59] op_sel_hi:[1,0]
	v_pk_mul_f32 v[0:1], v[0:1], v[58:59] op_sel_hi:[1,0]
	v_pk_add_f32 v[146:147], v[146:147], v[190:191]
	v_mul_f32_e32 v164, v164, v58
	v_mov_b32_e32 v153, v60
	v_mov_b32_e32 v157, v180
	v_mov_b32_e32 v51, v184
	v_mov_b32_e32 v55, v188
	v_mov_b32_e32 v33, v46
	v_mov_b32_e32 v35, v62
	v_mov_b32_e32 v39, v182
	v_mov_b32_e32 v43, v186
	s_branch .LBB0_652
.LBB0_647:
	s_waitcnt lgkmcnt(0)
	v_mfma_f32_32x32x16_bf16 v[48:63], v[108:111], v[68:71], 0
	s_andn2_b64 vcc, exec, s[2:3]
	v_mfma_f32_32x32x16_bf16 v[32:47], v[104:107], v[68:71], 0
	v_mfma_f32_32x32x16_bf16 v[48:63], v[100:103], v[64:67], v[48:63]
	v_mfma_f32_32x32x16_bf16 v[32:47], v[96:99], v[64:67], v[32:47]
	v_mfma_f32_32x32x16_bf16 v[48:63], v[92:95], v[76:79], v[48:63]
	v_mfma_f32_32x32x16_bf16 v[32:47], v[88:91], v[76:79], v[32:47]
	v_mfma_f32_32x32x16_bf16 v[48:63], v[84:87], v[72:75], v[48:63]
	v_mfma_f32_32x32x16_bf16 v[32:47], v[80:83], v[72:75], v[32:47]
	s_cbranch_vccz .Lgq_anym
.LBB0_649:
	s_add_i32 s10, s7, -1
	s_and_b32 s10, s10, 3
	s_mulk_i32 s10, 0x5000
	s_add_i32 s10, s10, 0
	s_and_b32 s11, s7, 3
	v_add3_u32 v80, s10, v178, v177
	s_mulk_i32 s11, 0x5000
	v_add3_u32 v80, v80, v160, s51
	v_add_u32_e32 v81, s11, v175
	ds_read_b64_tr_b16 v[112:113], v80 offset:0
	ds_read_b64_tr_b16 v[114:115], v80 offset:1024
	ds_read_b64_tr_b16 v[140:141], v80 offset:512
	ds_read_b64_tr_b16 v[142:143], v80 offset:1536
	ds_read_b64_tr_b16 v[116:117], v80 offset:2048
	ds_read_b64_tr_b16 v[118:119], v80 offset:3072
	ds_read_b64_tr_b16 v[136:137], v80 offset:2560
	ds_read_b64_tr_b16 v[138:139], v80 offset:3584
	ds_read_b64_tr_b16 v[124:125], v80 offset:4096
	ds_read_b64_tr_b16 v[126:127], v80 offset:5120
	ds_read_b64_tr_b16 v[132:133], v80 offset:4608
	ds_read_b64_tr_b16 v[134:135], v80 offset:5632
	ds_read_b64_tr_b16 v[120:121], v80 offset:6144
	ds_read_b64_tr_b16 v[122:123], v80 offset:7168
	ds_read_b64_tr_b16 v[128:129], v80 offset:6656
	ds_read_b64_tr_b16 v[130:131], v80 offset:7680
	v_add_u32_e32 v80, v81, v165
	ds_read_b128 v[108:111], v80
	ds_read_b128 v[104:107], v80 offset:4096
	v_add_u32_e32 v80, v81, v172
	ds_read_b128 v[100:103], v80
	ds_read_b128 v[96:99], v80 offset:4096
	v_add_u32_e32 v80, v81, v168
	ds_read_b128 v[92:95], v80
	ds_read_b128 v[88:91], v80 offset:4096
	v_add_u32_e32 v80, v81, v167
	ds_read_b128 v[84:87], v80
	ds_read_b128 v[80:83], v80 offset:4096
	v_exp_f32_e32 v152, v48
	v_exp_f32_e32 v32, v32
	v_exp_f32_e32 v48, v33
	v_exp_f32_e32 v153, v50
	v_exp_f32_e32 v33, v34
	v_exp_f32_e32 v154, v49
	v_exp_f32_e32 v155, v51
	v_exp_f32_e32 v49, v35
	v_exp_f32_e32 v156, v52
	v_exp_f32_e32 v34, v36
	v_exp_f32_e32 v157, v54
	v_exp_f32_e32 v35, v38
	v_exp_f32_e32 v158, v53
	v_exp_f32_e32 v36, v37
	v_exp_f32_e32 v159, v55
	v_exp_f32_e32 v37, v39
	v_exp_f32_e32 v50, v56
	v_exp_f32_e32 v38, v40
	v_exp_f32_e32 v51, v58
	v_exp_f32_e32 v39, v42
	v_exp_f32_e32 v52, v57
	v_exp_f32_e32 v40, v41
	v_exp_f32_e32 v53, v59
	v_exp_f32_e32 v41, v43
	v_exp_f32_e32 v42, v44
	v_exp_f32_e32 v44, v45
	v_exp_f32_e32 v43, v46
	v_exp_f32_e32 v45, v47
	v_pk_add_f32 v[46:47], v[152:153], v[32:33]
	v_exp_f32_e32 v54, v60
	v_exp_f32_e32 v56, v61
	v_exp_f32_e32 v55, v62
	v_pk_add_f32 v[46:47], v[46:47], 0 op_sel_hi:[1,0]
	v_pk_add_f32 v[58:59], v[154:155], v[48:49]
	v_pk_add_f32 v[60:61], v[156:157], v[34:35]
	v_exp_f32_e32 v57, v63
	v_pk_add_f32 v[58:59], v[58:59], 0 op_sel_hi:[1,0]
	v_pk_add_f32 v[46:47], v[60:61], v[46:47]
	v_pk_add_f32 v[60:61], v[158:159], v[36:37]
	s_nop 0
	v_pk_add_f32 v[58:59], v[60:61], v[58:59]
	v_pk_add_f32 v[60:61], v[50:51], v[38:39]
	s_nop 0
	v_pk_add_f32 v[46:47], v[60:61], v[46:47]
	v_pk_add_f32 v[60:61], v[52:53], v[40:41]
	s_nop 0
	v_pk_add_f32 v[58:59], v[60:61], v[58:59]
	v_pk_add_f32 v[60:61], v[54:55], v[42:43]
	s_nop 0
	v_pk_add_f32 v[46:47], v[60:61], v[46:47]
	v_pk_add_f32 v[60:61], v[56:57], v[44:45]
	s_nop 0
	v_pk_add_f32 v[58:59], v[60:61], v[58:59]
	s_nop 0
	v_pk_add_f32 v[46:47], v[46:47], v[58:59]
	s_nop 0
	v_pk_add_f32 v[46:47], v[46:47], v[46:47] op_sel:[0,1] op_sel_hi:[1,0]
	s_nop 0
	v_cmp_ngt_f32_e32 vcc, s92, v46
	s_cbranch_vccnz .Lgq_slow

.LBB0_652:
	s_add_i32 s12, s7, 2
	s_cmp_ge_u32 s12, s19
	s_cselect_b64 s[10:11], -1, 0
	s_cbranch_scc1 .LBB0_654
	s_and_b32 s12, s12, 3
	s_mulk_i32 s12, 0x5000
	s_add_i32 s12, s5, s12
	s_mov_b32 m0, s12
	s_nop 0
	global_load_lds_dwordx4 v[148:149], off
	s_add_i32 m0, s12, 0x3000
	s_nop 0
	global_load_lds_dwordx4 v[150:151], off
.LBB0_654:
	v_cvt_pk_bf16_f32 v58, v152, v154
	v_cvt_pk_bf16_f32 v59, v153, v155
	v_cvt_pk_bf16_f32 v60, v156, v158
	v_cvt_pk_bf16_f32 v61, v157, v159
	s_waitcnt lgkmcnt(0)
	v_cvt_pk_bf16_f32 v50, v50, v52
	v_cvt_pk_bf16_f32 v51, v51, v53
	v_mfma_f32_32x32x16_bf16 v[16:31], v[140:143], v[58:61], v[16:31]
	v_cvt_pk_bf16_f32 v52, v54, v56
	v_cvt_pk_bf16_f32 v53, v55, v57
	v_cvt_pk_bf16_f32 v32, v32, v48
	v_cvt_pk_bf16_f32 v33, v33, v49
	v_cvt_pk_bf16_f32 v34, v34, v36
	v_cvt_pk_bf16_f32 v35, v35, v37
	v_cvt_pk_bf16_f32 v36, v38, v40
	v_mfma_f32_32x32x16_bf16 v[0:15], v[112:115], v[58:61], v[0:15]
	v_cvt_pk_bf16_f32 v37, v39, v41
	v_cvt_pk_bf16_f32 v38, v42, v44
	v_cvt_pk_bf16_f32 v39, v43, v45
	s_and_b64 vcc, exec, s[10:11]
	v_mfma_f32_32x32x16_bf16 v[16:31], v[136:139], v[50:53], v[16:31]
	v_mfma_f32_32x32x16_bf16 v[0:15], v[116:119], v[50:53], v[0:15]
	v_mfma_f32_32x32x16_bf16 v[16:31], v[132:135], v[32:35], v[16:31]
	v_mfma_f32_32x32x16_bf16 v[0:15], v[124:127], v[32:35], v[0:15]
	v_mfma_f32_32x32x16_bf16 v[16:31], v[128:131], v[36:39], v[16:31]
	v_mfma_f32_32x32x16_bf16 v[0:15], v[120:123], v[36:39], v[0:15]
	s_cbranch_vccnz .Lgq_lastwait
	s_waitcnt vmcnt(2)
.Lgq_bar:
	s_barrier
	s_add_i32 s7, s7, 1
	v_add_f32_e32 v164, v164, v146
	v_lshl_add_u64 v[148:149], v[148:149], 0, s[94:95]
	s_cmp_lg_u32 s19, s7
	v_lshl_add_u64 v[150:151], v[150:151], 0, s[94:95]
	s_cbranch_scc1 .LBB0_647

.Lml_w2:
	s_waitcnt vmcnt(2)
	s_barrier
	s_add_i32 s7, s7, 1
	s_add_i32 s14, s21, s7
	v_add_f32_e32 v185, v185, v154
	v_lshl_add_u64 v[156:157], v[156:157], 0, s[94:95]
	v_lshl_add_u64 v[158:159], v[158:159], 0, s[94:95]
	s_cmp_lg_u32 s14, 4
	v_lshl_add_u64 v[172:173], v[172:173], 0, s[94:95]
	s_cbranch_scc1 .LBB0_680
	s_branch .LBB0_694
.Lml_anym:
	s_nop 9
	v_sub_f32_e32 v47, v47, v155
	v_sub_f32_e32 v46, v46, v155
	v_sub_f32_e32 v45, v45, v155
	v_sub_f32_e32 v44, v44, v155
	v_sub_f32_e32 v43, v43, v155
	v_sub_f32_e32 v42, v42, v155
	v_sub_f32_e32 v41, v41, v155
	v_sub_f32_e32 v40, v40, v155
	v_sub_f32_e32 v39, v39, v155
	v_sub_f32_e32 v38, v38, v155
	v_sub_f32_e32 v37, v37, v155
	v_sub_f32_e32 v36, v36, v155
	v_sub_f32_e32 v35, v35, v155
	v_sub_f32_e32 v34, v34, v155
	v_sub_f32_e32 v33, v33, v155
	v_sub_f32_e32 v32, v32, v155
	v_sub_f32_e32 v63, v63, v155
	v_sub_f32_e32 v62, v62, v155
	v_sub_f32_e32 v61, v61, v155
	v_sub_f32_e32 v60, v60, v155
	v_sub_f32_e32 v59, v59, v155
	v_sub_f32_e32 v58, v58, v155
	v_sub_f32_e32 v57, v57, v155
	v_sub_f32_e32 v56, v56, v155
	v_sub_f32_e32 v55, v55, v155
	v_sub_f32_e32 v54, v54, v155
	v_sub_f32_e32 v53, v53, v155
	v_sub_f32_e32 v52, v52, v155
	v_sub_f32_e32 v51, v51, v155
	v_sub_f32_e32 v50, v50, v155
	v_sub_f32_e32 v49, v49, v155
	v_sub_f32_e32 v48, v48, v155
	s_branch .LBB0_682
.Lml_slow:
	v_add_u32_e32 v154, s14, v183
	v_add_u32_e32 v48, v154, v169
	ds_read_b128 v[32:35], v48
	v_add_u32_e32 v178, v154, v167
	ds_read_b128 v[174:177], v178
	ds_read_b128 v[48:51], v48 offset:4096
	s_mov_b64 s[12:13], -1
	s_waitcnt lgkmcnt(0)
	v_mfma_f32_32x32x16_bf16 v[32:47], v[32:35], v[84:87], 0
	v_mfma_f32_32x32x16_bf16 v[32:47], v[174:177], v[80:83], v[32:47]
	ds_read_b128 v[174:177], v178 offset:4096
	v_add_u32_e32 v178, v154, v165
	v_add_u32_e32 v154, v154, v163
	v_mfma_f32_32x32x16_bf16 v[48:63], v[48:51], v[84:87], 0
	s_waitcnt lgkmcnt(0)
	v_mfma_f32_32x32x16_bf16 v[48:63], v[174:177], v[80:83], v[48:63]
	ds_read_b128 v[174:177], v178
	s_waitcnt lgkmcnt(0)
	v_mfma_f32_32x32x16_bf16 v[32:47], v[174:177], v[76:79], v[32:47]
	ds_read_b128 v[174:177], v178 offset:4096
	s_waitcnt lgkmcnt(0)
	v_mfma_f32_32x32x16_bf16 v[48:63], v[174:177], v[76:79], v[48:63]
	ds_read_b128 v[174:177], v154
	s_waitcnt lgkmcnt(0)
	v_mfma_f32_32x32x16_bf16 v[32:47], v[174:177], v[72:75], v[32:47]
	ds_read_b128 v[174:177], v154 offset:4096
	s_waitcnt lgkmcnt(0)
	v_mfma_f32_32x32x16_bf16 v[48:63], v[174:177], v[72:75], v[48:63]
	ds_read_b128 v[174:177], v193 offset:8192
	s_waitcnt lgkmcnt(0)
	v_mfma_f32_32x32x16_bf16 v[32:47], v[174:177], v[68:71], v[32:47]
	ds_read_b128 v[174:177], v193 offset:10240
	s_waitcnt lgkmcnt(0)
	v_mfma_f32_32x32x16_bf16 v[48:63], v[174:177], v[68:71], v[48:63]
	ds_read_b128 v[174:177], v192 offset:8192
	s_waitcnt lgkmcnt(0)
	v_mfma_f32_32x32x16_bf16 v[32:47], v[174:177], v[64:67], v[32:47]
	ds_read_b128 v[174:177], v192 offset:10240
	s_waitcnt lgkmcnt(0)
	v_mfma_f32_32x32x16_bf16 v[48:63], v[174:177], v[64:67], v[48:63]
	s_nop 8
	v_sub_f32_e32 v32, v32, v155
	v_sub_f32_e32 v33, v33, v155
	v_sub_f32_e32 v34, v34, v155
	v_sub_f32_e32 v175, v35, v155
	v_sub_f32_e32 v36, v36, v155
	v_sub_f32_e32 v180, v37, v155
	v_sub_f32_e32 v38, v38, v155
	v_sub_f32_e32 v48, v48, v155
	v_sub_f32_e32 v49, v49, v155
	v_max_f32_e32 v154, v32, v48
	v_max_f32_e32 v174, v33, v49
	v_sub_f32_e32 v50, v50, v155
	v_sub_f32_e32 v51, v51, v155
	v_max3_f32 v154, v154, s93, v174
	v_max_f32_e32 v174, v34, v50
	v_max_f32_e32 v35, v175, v51
	v_sub_f32_e32 v52, v52, v155
	v_sub_f32_e32 v53, v53, v155
	v_max3_f32 v35, v154, v174, v35
	v_max_f32_e32 v154, v36, v52
	v_max_f32_e32 v37, v180, v53
	v_max3_f32 v35, v35, v154, v37
	v_sub_f32_e32 v54, v54, v155
	v_sub_f32_e32 v154, v39, v155
	v_sub_f32_e32 v55, v55, v155
	v_max_f32_e32 v37, v38, v54
	v_max_f32_e32 v39, v154, v55
	v_sub_f32_e32 v40, v40, v155
	v_sub_f32_e32 v56, v56, v155
	v_sub_f32_e32 v196, v41, v155
	v_sub_f32_e32 v57, v57, v155
	v_max3_f32 v35, v35, v37, v39
	v_max_f32_e32 v37, v40, v56
	v_max_f32_e32 v39, v196, v57
	v_sub_f32_e32 v42, v42, v155
	v_sub_f32_e32 v198, v58, v155
	v_sub_f32_e32 v199, v43, v155
	v_sub_f32_e32 v59, v59, v155
	v_max3_f32 v35, v35, v37, v39
	v_max_f32_e32 v37, v42, v198
	v_max_f32_e32 v39, v199, v59
	v_sub_f32_e32 v44, v44, v155
	v_sub_f32_e32 v200, v60, v155
	v_sub_f32_e32 v201, v45, v155
	v_sub_f32_e32 v202, v61, v155
	v_max3_f32 v35, v35, v37, v39
	v_max_f32_e32 v37, v44, v200
	v_max_f32_e32 v39, v201, v202
	v_sub_f32_e32 v203, v46, v155
	v_sub_f32_e32 v204, v62, v155
	v_sub_f32_e32 v205, v47, v155
	v_sub_f32_e32 v206, v63, v155
	v_max3_f32 v35, v35, v37, v39
	v_max_f32_e32 v37, v203, v204
	v_max_f32_e32 v39, v205, v206
	v_max3_f32 v35, v35, v37, v39
	v_mov_b32_e32 v37, v35
	s_nop 1
	v_permlane32_swap_b32_e32 v35, v37
	v_max3_f32 v207, v35, v37, 0
	v_sub_f32_e32 v32, v32, v207
	v_sub_f32_e32 v33, v33, v207
	v_exp_f32_e32 v174, v32
	v_sub_f32_e32 v32, v48, v207
	v_exp_f32_e32 v176, v33
	v_sub_f32_e32 v33, v49, v207
	v_exp_f32_e32 v32, v32
	v_exp_f32_e32 v48, v33
	v_sub_f32_e32 v33, v34, v207
	v_exp_f32_e32 v60, v33
	v_sub_f32_e32 v33, v50, v207
	v_exp_f32_e32 v46, v33
	v_add_f32_e32 v35, v174, v32
	v_sub_f32_e32 v33, v175, v207
	v_add_f32_e32 v47, 0, v35
	v_add_f32_e32 v61, v176, v48
	v_exp_f32_e32 v177, v33
	v_sub_f32_e32 v33, v51, v207
	v_pk_add_f32 v[34:35], v[60:61], v[46:47]
	v_exp_f32_e32 v49, v33
	v_sub_f32_e32 v33, v36, v207
	v_pk_add_f32 v[34:35], v[34:35], v[34:35] op_sel_hi:[0,1]
	v_exp_f32_e32 v178, v33
	v_sub_f32_e32 v33, v52, v207
	v_exp_f32_e32 v34, v33
	v_add_f32_e32 v179, v177, v49
	v_sub_f32_e32 v33, v180, v207
	v_exp_f32_e32 v180, v33
	v_pk_add_f32 v[36:37], v[178:179], v[34:35]
	v_sub_f32_e32 v33, v53, v207
	v_pk_add_f32 v[62:63], v[36:37], v[36:37] op_sel_hi:[0,1]
	v_exp_f32_e32 v36, v33
	v_sub_f32_e32 v33, v38, v207
	v_exp_f32_e32 v192, v33
	v_sub_f32_e32 v33, v54, v207
	v_exp_f32_e32 v62, v33
	v_sub_f32_e32 v33, v154, v207
	v_add_f32_e32 v193, v180, v36
	v_exp_f32_e32 v181, v33
	v_sub_f32_e32 v33, v55, v207
	v_pk_add_f32 v[38:39], v[192:193], v[62:63]
	v_exp_f32_e32 v37, v33
	v_sub_f32_e32 v33, v40, v207
	v_pk_add_f32 v[38:39], v[38:39], v[38:39] op_sel_hi:[0,1]
	v_exp_f32_e32 v50, v33
	v_sub_f32_e32 v33, v56, v207
	v_exp_f32_e32 v38, v33
	v_add_f32_e32 v51, v181, v37
	v_sub_f32_e32 v33, v196, v207
	v_exp_f32_e32 v52, v33
	v_pk_add_f32 v[40:41], v[50:51], v[38:39]
	v_sub_f32_e32 v33, v57, v207
	v_pk_add_f32 v[194:195], v[40:41], v[40:41] op_sel_hi:[0,1]
	v_exp_f32_e32 v40, v33
	v_sub_f32_e32 v33, v42, v207
	v_exp_f32_e32 v196, v33
	v_sub_f32_e32 v33, v198, v207
	v_exp_f32_e32 v194, v33
	v_sub_f32_e32 v33, v199, v207
	v_add_f32_e32 v197, v52, v40
	v_exp_f32_e32 v53, v33
	v_sub_f32_e32 v33, v59, v207
	v_pk_add_f32 v[42:43], v[196:197], v[194:195]
	v_exp_f32_e32 v41, v33
	v_sub_f32_e32 v33, v44, v207
	v_pk_add_f32 v[42:43], v[42:43], v[42:43] op_sel_hi:[0,1]
	v_exp_f32_e32 v54, v33
	v_sub_f32_e32 v33, v200, v207
	v_exp_f32_e32 v42, v33
	v_add_f32_e32 v55, v53, v41
	v_sub_f32_e32 v33, v201, v207
	v_exp_f32_e32 v56, v33
	v_pk_add_f32 v[44:45], v[54:55], v[42:43]
	v_sub_f32_e32 v33, v202, v207
	v_pk_add_f32 v[198:199], v[44:45], v[44:45] op_sel_hi:[0,1]
	v_exp_f32_e32 v44, v33
	v_sub_f32_e32 v33, v203, v207
	v_exp_f32_e32 v200, v33
	v_sub_f32_e32 v33, v204, v207
	v_exp_f32_e32 v198, v33
	v_sub_f32_e32 v33, v205, v207
	v_exp_f32_e32 v57, v33
	v_sub_f32_e32 v33, v206, v207
	v_exp_f32_e32 v45, v33
	v_exp_f32_e64 v58, -v207
	v_add_f32_e32 v201, v56, v44
	v_pk_add_f32 v[202:203], v[200:201], v[198:199]
	v_add_f32_e32 v154, v57, v45
	v_pk_add_f32 v[202:203], v[202:203], v[202:203] op_sel:[0,1] op_sel_hi:[1,0]
	v_pk_mul_f32 v[14:15], v[14:15], v[58:59] op_sel_hi:[1,0]
	v_mov_b32_e32 v203, v207
	v_pk_mul_f32 v[12:13], v[12:13], v[58:59] op_sel_hi:[1,0]
	v_pk_mul_f32 v[10:11], v[10:11], v[58:59] op_sel_hi:[1,0]
	v_pk_mul_f32 v[8:9], v[8:9], v[58:59] op_sel_hi:[1,0]
	v_pk_mul_f32 v[6:7], v[6:7], v[58:59] op_sel_hi:[1,0]
	v_pk_mul_f32 v[4:5], v[4:5], v[58:59] op_sel_hi:[1,0]
	v_pk_mul_f32 v[2:3], v[2:3], v[58:59] op_sel_hi:[1,0]
	v_pk_mul_f32 v[0:1], v[0:1], v[58:59] op_sel_hi:[1,0]
	v_pk_mul_f32 v[30:31], v[30:31], v[58:59] op_sel_hi:[1,0]
	v_pk_mul_f32 v[28:29], v[28:29], v[58:59] op_sel_hi:[1,0]
	v_pk_mul_f32 v[26:27], v[26:27], v[58:59] op_sel_hi:[1,0]
	v_pk_mul_f32 v[24:25], v[24:25], v[58:59] op_sel_hi:[1,0]
	v_pk_mul_f32 v[22:23], v[22:23], v[58:59] op_sel_hi:[1,0]
	v_pk_mul_f32 v[20:21], v[20:21], v[58:59] op_sel_hi:[1,0]
	v_pk_mul_f32 v[18:19], v[18:19], v[58:59] op_sel_hi:[1,0]
	v_pk_mul_f32 v[16:17], v[16:17], v[58:59] op_sel_hi:[1,0]
	v_pk_add_f32 v[154:155], v[154:155], v[202:203]
	v_mul_f32_e32 v185, v185, v58
	v_mov_b32_e32 v175, v60
	v_mov_b32_e32 v179, v192
	v_mov_b32_e32 v51, v196
	v_mov_b32_e32 v55, v200
	v_mov_b32_e32 v33, v46
	v_mov_b32_e32 v35, v62
	v_mov_b32_e32 v39, v194
	v_mov_b32_e32 v43, v198
	s_cmp_ge_u32 s7, s19
	s_cselect_b64 s[14:15], -1, 0
	s_and_b64 vcc, exec, s[14:15]
	s_cbranch_vccz .LBB0_685
	s_branch .LBB0_687
.LBB0_680:
	s_waitcnt lgkmcnt(0)
	v_mfma_f32_32x32x16_bf16 v[32:47], v[116:119], v[84:87], 0
	s_add_i32 s14, s7, -3
	s_and_b32 s14, s14, 3
	s_mulk_i32 s14, 0x5000
	s_add_i32 s14, s14, 0
	v_add_u32_e32 v116, s14, v186
	v_mfma_f32_32x32x16_bf16 v[32:47], v[112:115], v[80:83], v[32:47]
	v_mfma_f32_32x32x16_bf16 v[48:63], v[108:111], v[84:87], 0
	v_add_u32_e32 v193, v116, v190
	v_add_u32_e32 v192, v116, v191
	ds_read_b128 v[108:111], v193 offset:8192
	ds_read_b128 v[112:115], v193 offset:10240
	ds_read_b128 v[116:119], v192 offset:8192
	ds_read_b128 v[120:123], v192 offset:10240
	v_mfma_f32_32x32x16_bf16 v[48:63], v[104:107], v[80:83], v[48:63]
	v_mfma_f32_32x32x16_bf16 v[32:47], v[100:103], v[76:79], v[32:47]
	s_andn2_b64 vcc, exec, s[12:13]
	v_mfma_f32_32x32x16_bf16 v[48:63], v[96:99], v[76:79], v[48:63]
	v_mfma_f32_32x32x16_bf16 v[32:47], v[92:95], v[72:75], v[32:47]
	v_mfma_f32_32x32x16_bf16 v[48:63], v[88:91], v[72:75], v[48:63]
	s_waitcnt lgkmcnt(0)
	v_mfma_f32_32x32x16_bf16 v[32:47], v[108:111], v[68:71], v[32:47]
	v_mfma_f32_32x32x16_bf16 v[48:63], v[112:115], v[68:71], v[48:63]
	v_mfma_f32_32x32x16_bf16 v[32:47], v[116:119], v[64:67], v[32:47]
	v_mfma_f32_32x32x16_bf16 v[48:63], v[120:123], v[64:67], v[48:63]
	s_cbranch_vccz .Lml_anym
.LBB0_682:
	s_add_i32 s15, s7, -2
	s_and_b32 s15, s15, 3
	v_add3_u32 v88, s14, v187, v188
	s_mulk_i32 s15, 0x5000
	v_add3_u32 v88, v88, v160, s51
	v_add_u32_e32 v89, s15, v189
	ds_read_b64_tr_b16 v[120:121], v88 offset:0
	ds_read_b64_tr_b16 v[122:123], v88 offset:1024
	ds_read_b64_tr_b16 v[148:149], v88 offset:512
	ds_read_b64_tr_b16 v[150:151], v88 offset:1536
	ds_read_b64_tr_b16 v[124:125], v88 offset:2048
	ds_read_b64_tr_b16 v[126:127], v88 offset:3072
	ds_read_b64_tr_b16 v[144:145], v88 offset:2560
	ds_read_b64_tr_b16 v[146:147], v88 offset:3584
	ds_read_b64_tr_b16 v[132:133], v88 offset:4096
	ds_read_b64_tr_b16 v[134:135], v88 offset:5120
	ds_read_b64_tr_b16 v[140:141], v88 offset:4608
	ds_read_b64_tr_b16 v[142:143], v88 offset:5632
	ds_read_b64_tr_b16 v[128:129], v88 offset:6144
	ds_read_b64_tr_b16 v[130:131], v88 offset:7168
	ds_read_b64_tr_b16 v[136:137], v88 offset:6656
	ds_read_b64_tr_b16 v[138:139], v88 offset:7680
	v_add_u32_e32 v88, v89, v169
	ds_read_b128 v[116:119], v88
	ds_read_b128 v[108:111], v88 offset:4096
	v_add_u32_e32 v88, v89, v167
	ds_read_b128 v[112:115], v88
	ds_read_b128 v[104:107], v88 offset:4096
	v_add_u32_e32 v88, v89, v165
	ds_read_b128 v[100:103], v88
	ds_read_b128 v[96:99], v88 offset:4096
	v_add_u32_e32 v88, v89, v163
	ds_read_b128 v[92:95], v88
	ds_read_b128 v[88:91], v88 offset:4096
	v_exp_f32_e32 v174, v32
	v_exp_f32_e32 v32, v48
	v_exp_f32_e32 v176, v33
	v_exp_f32_e32 v175, v34
	v_exp_f32_e32 v33, v50
	v_exp_f32_e32 v48, v49
	v_exp_f32_e32 v177, v35
	v_exp_f32_e32 v49, v51
	v_exp_f32_e32 v178, v36
	v_exp_f32_e32 v34, v52
	v_exp_f32_e32 v179, v38
	v_exp_f32_e32 v35, v54
	v_exp_f32_e32 v180, v37
	v_exp_f32_e32 v36, v53
	v_exp_f32_e32 v181, v39
	v_exp_f32_e32 v37, v55
	v_exp_f32_e32 v50, v40
	v_exp_f32_e32 v38, v56
	v_exp_f32_e32 v51, v42
	v_exp_f32_e32 v39, v58
	v_exp_f32_e32 v52, v41
	v_exp_f32_e32 v40, v57
	v_exp_f32_e32 v53, v43
	v_exp_f32_e32 v41, v59
	v_exp_f32_e32 v55, v46
	v_exp_f32_e32 v57, v47
	v_pk_add_f32 v[46:47], v[174:175], v[32:33]
	v_exp_f32_e32 v54, v44
	v_exp_f32_e32 v42, v60
	v_exp_f32_e32 v44, v61
	v_exp_f32_e32 v43, v62
	v_pk_add_f32 v[46:47], v[46:47], 0 op_sel_hi:[1,0]
	v_pk_add_f32 v[58:59], v[176:177], v[48:49]
	v_pk_add_f32 v[60:61], v[178:179], v[34:35]
	v_exp_f32_e32 v56, v45
	v_exp_f32_e32 v45, v63
	v_pk_add_f32 v[58:59], v[58:59], 0 op_sel_hi:[1,0]
	v_pk_add_f32 v[46:47], v[60:61], v[46:47]
	v_pk_add_f32 v[60:61], v[180:181], v[36:37]
	s_nop 0
	v_pk_add_f32 v[58:59], v[60:61], v[58:59]
	v_pk_add_f32 v[60:61], v[50:51], v[38:39]
	s_nop 0
	v_pk_add_f32 v[46:47], v[60:61], v[46:47]
	v_pk_add_f32 v[60:61], v[52:53], v[40:41]
	s_nop 0
	v_pk_add_f32 v[58:59], v[60:61], v[58:59]
	v_pk_add_f32 v[60:61], v[54:55], v[42:43]
	s_nop 0
	v_pk_add_f32 v[46:47], v[60:61], v[46:47]
	v_pk_add_f32 v[60:61], v[56:57], v[44:45]
	s_nop 0
	v_pk_add_f32 v[58:59], v[60:61], v[58:59]
	s_nop 0
	v_pk_add_f32 v[46:47], v[46:47], v[58:59]
	s_nop 0
	v_pk_add_f32 v[46:47], v[46:47], v[46:47] op_sel:[0,1] op_sel_hi:[1,0]
	s_nop 0
	v_cmp_ngt_f32_e32 vcc, s92, v46
	s_cbranch_vccnz .Lml_slow
.LBB0_684:
	v_mov_b32_e32 v154, v46
	s_cmp_ge_u32 s7, s19
	s_cselect_b64 s[14:15], -1, 0
	s_cbranch_scc1 .LBB0_687

.LBB0_687:
	v_cvt_pk_bf16_f32 v58, v174, v176
	v_cvt_pk_bf16_f32 v59, v175, v177
	v_cvt_pk_bf16_f32 v60, v178, v180
	v_cvt_pk_bf16_f32 v61, v179, v181
	s_waitcnt lgkmcnt(0)
	v_cvt_pk_bf16_f32 v50, v50, v52
	v_cvt_pk_bf16_f32 v51, v51, v53
	v_mfma_f32_32x32x16_bf16 v[0:15], v[148:151], v[58:61], v[0:15]
	v_cvt_pk_bf16_f32 v52, v54, v56
	v_cvt_pk_bf16_f32 v53, v55, v57
	v_cvt_pk_bf16_f32 v32, v32, v48
	v_cvt_pk_bf16_f32 v33, v33, v49
	v_cvt_pk_bf16_f32 v34, v34, v36
	v_cvt_pk_bf16_f32 v35, v35, v37
	v_cvt_pk_bf16_f32 v36, v38, v40
	v_mfma_f32_32x32x16_bf16 v[16:31], v[120:123], v[58:61], v[16:31]
	v_cvt_pk_bf16_f32 v37, v39, v41
	v_cvt_pk_bf16_f32 v38, v42, v44
	v_cvt_pk_bf16_f32 v39, v43, v45
	s_and_b64 vcc, exec, s[14:15]
	v_mfma_f32_32x32x16_bf16 v[0:15], v[144:147], v[50:53], v[0:15]
	v_mfma_f32_32x32x16_bf16 v[16:31], v[124:127], v[50:53], v[16:31]
	v_mfma_f32_32x32x16_bf16 v[0:15], v[140:143], v[32:35], v[0:15]
	v_mfma_f32_32x32x16_bf16 v[16:31], v[132:135], v[32:35], v[16:31]
	v_mfma_f32_32x32x16_bf16 v[0:15], v[136:139], v[36:39], v[0:15]
	v_mfma_f32_32x32x16_bf16 v[16:31], v[128:131], v[36:39], v[16:31]
	s_cbranch_vccnz .Lml_lastwait
	s_and_b64 vcc, exec, s[2:3]
	s_cbranch_vccnz .Lml_w2
	s_waitcnt vmcnt(3)
.Lml_bar:
	s_barrier
	s_add_i32 s7, s7, 1
	s_add_i32 s14, s21, s7
	v_add_f32_e32 v185, v185, v154
	v_lshl_add_u64 v[156:157], v[156:157], 0, s[94:95]
	v_lshl_add_u64 v[158:159], v[158:159], 0, s[94:95]
	s_cmp_lg_u32 s14, 4
	v_lshl_add_u64 v[172:173], v[172:173], 0, s[94:95]
	s_cbranch_scc1 .LBB0_680
